# v28 + grid-barrier poll back-off: s_sleep 1 -> s_sleep 4 between polls of the generation word (fewer polling loads while stragglers finish)
# baseline (speedup 1.0000x reference)
.LBB0_1904:
	s_and_b32 s25, s24, 0xff
	s_mov_b64 s[40:41], -1
	s_cmp_lg_u32 s25, 0
	s_mov_b64 s[44:45], -1
	s_sleep 4
	s_cbranch_scc0 .LBB0_1907
	s_and_b64 vcc, exec, s[44:45]
	s_cbranch_vccz .LBB0_1903
